# D attention unit epilogue: the 16 sub-layer-norm gain loads issued together in own registers instead of load-wait-scale-store sixteen times
# baseline (speedup 1.0000x reference)
; #define LAS __attribute__((address_space(3)))
; DI void attn_unit_d32(const Ctx& C, const bf16_t* __restrict__ Z, bf16_t* __restrict__ Y, int b, int qsel, int hsel, bool ctxq, float lam, float post_scale, const float* subln, const float mref) {
;     ...
;     __syncthreads();
;     if (sm == 0) {
;         f32x4 r[4][4]; float ss = 0.f;
; #pragma unroll
;         for (int d = 0; d < 4; ++d)
; #pragma unroll
;             for (int g = 0; g < 4; ++g) { const f32x4 x2 = *(const LAS f32x4*)(X + 32 * d + 8 * g + 4 * hh);
;                 const f32x4 x1 = {o[d][4 * g] * linv, o[d][4 * g + 1] * linv, o[d][4 * g + 2] * linv, o[d][4 * g + 3] * linv};
;                 r[d][g] = x1 - x2 * lam; ss += (r[d][g][0] * r[d][g][0] + r[d][g][1] * r[d][g][1]) + (r[d][g][2] * r[d][g][2] + r[d][g][3] * r[d][g][3]); }
.LBB0_410:
	s_andn2_b64 vcc, exec, s[14:15]
	s_waitcnt lgkmcnt(0)
	s_barrier
	s_cbranch_vccnz .LBB0_396
	ds_read_b128 v[84:87], v190
	ds_read_b128 v[98:101], v190 offset:32
	v_xor_b32_e32 v96, 0x80000000, v168
	v_pk_mul_f32 v[68:69], v[68:69], v[0:1] op_sel_hi:[1,0]
	v_pk_mul_f32 v[70:71], v[70:71], v[0:1] op_sel_hi:[1,0]
	v_mov_b32_e32 v97, v96
	s_waitcnt lgkmcnt(1)
	v_pk_fma_f32 v[92:93], v[96:97], v[86:87], v[70:71]
	v_pk_fma_f32 v[94:95], v[168:169], v[84:85], v[68:69] neg_lo:[1,0,0] neg_hi:[1,0,0]
	v_pk_mul_f32 v[68:69], v[92:93], v[92:93]
	v_pk_mul_f32 v[70:71], v[94:95], v[94:95]
	v_pk_mul_f32 v[52:53], v[52:53], v[0:1] op_sel_hi:[1,0]
	v_pk_mov_b32 v[84:85], v[70:71], v[68:69] op_sel:[1,0]
	v_mov_b32_e32 v71, v69
	v_pk_add_f32 v[102:103], v[84:85], v[70:71]
	v_pk_mul_f32 v[68:69], v[72:73], v[0:1] op_sel_hi:[1,0]
	v_pk_mul_f32 v[70:71], v[74:75], v[0:1] op_sel_hi:[1,0]
	s_waitcnt lgkmcnt(0)
	v_pk_fma_f32 v[90:91], v[168:169], v[98:99], v[68:69] neg_lo:[1,0,0] neg_hi:[1,0,0]
	v_pk_fma_f32 v[88:89], v[96:97], v[100:101], v[70:71]
	v_pk_mul_f32 v[70:71], v[90:91], v[90:91]
	v_pk_mul_f32 v[68:69], v[88:89], v[88:89]
	v_pk_mul_f32 v[74:75], v[76:77], v[0:1] op_sel_hi:[1,0]
	v_pk_mov_b32 v[72:73], v[70:71], v[68:69] op_sel:[1,0]
	v_mov_b32_e32 v71, v69
	v_pk_add_f32 v[72:73], v[72:73], v[70:71]
	ds_read_b128 v[68:71], v190 offset:64
	v_pk_mul_f32 v[76:77], v[78:79], v[0:1] op_sel_hi:[1,0]
	v_pk_mul_f32 v[54:55], v[54:55], v[0:1] op_sel_hi:[1,0]
	v_pk_mul_f32 v[56:57], v[56:57], v[0:1] op_sel_hi:[1,0]
	v_pk_mul_f32 v[58:59], v[58:59], v[0:1] op_sel_hi:[1,0]
	s_waitcnt lgkmcnt(0)
	v_pk_fma_f32 v[84:85], v[96:97], v[70:71], v[76:77]
	v_pk_fma_f32 v[86:87], v[168:169], v[68:69], v[74:75] neg_lo:[1,0,0] neg_hi:[1,0,0]
	ds_read_b128 v[68:71], v190 offset:96
	v_pk_mul_f32 v[74:75], v[80:81], v[0:1] op_sel_hi:[1,0]
	v_pk_mul_f32 v[76:77], v[82:83], v[0:1] op_sel_hi:[1,0]
	v_pk_mul_f32 v[36:37], v[36:37], v[0:1] op_sel_hi:[1,0]
	v_pk_mul_f32 v[38:39], v[38:39], v[0:1] op_sel_hi:[1,0]
	s_waitcnt lgkmcnt(0)
	v_pk_fma_f32 v[78:79], v[168:169], v[68:69], v[74:75] neg_lo:[1,0,0] neg_hi:[1,0,0]
	v_pk_fma_f32 v[76:77], v[96:97], v[70:71], v[76:77]
	v_mul_f32_e32 v70, v78, v78
	v_pk_add_f32 v[68:69], v[102:103], v[102:103] op_sel:[0,1] op_sel_hi:[1,0]
	v_mul_f32_e32 v74, v79, v79
	v_mov_b32_e32 v69, v70
	v_pk_add_f32 v[70:71], v[72:73], v[72:73] op_sel:[0,1] op_sel_hi:[1,0]
	v_mul_f32_e32 v72, v85, v85
	v_mov_b32_e32 v71, v74
	v_pk_add_f32 v[68:69], v[68:69], v[70:71]
	v_mul_f32_e32 v70, v87, v87
	v_mul_f32_e32 v75, v76, v76
	v_mul_f32_e32 v80, v77, v77
	v_pk_fma_f32 v[70:71], v[86:87], v[86:87], v[70:71] op_sel_hi:[1,1,0]
	v_pk_fma_f32 v[72:73], v[84:85], v[84:85], v[72:73] op_sel_hi:[1,1,0]
	v_mov_b32_e32 v71, v75
	v_mov_b32_e32 v73, v80
	v_pk_add_f32 v[70:71], v[70:71], v[72:73]
	v_pk_mul_f32 v[40:41], v[40:41], v[0:1] op_sel_hi:[1,0]
	v_pk_add_f32 v[80:81], v[68:69], v[70:71]
	ds_read_b128 v[70:73], v190 offset:128
	v_pk_mul_f32 v[42:43], v[42:43], v[0:1] op_sel_hi:[1,0]
	v_pk_mul_f32 v[24:25], v[24:25], v[0:1] op_sel_hi:[1,0]
	v_pk_mul_f32 v[26:27], v[26:27], v[0:1] op_sel_hi:[1,0]
	v_pk_mul_f32 v[28:29], v[28:29], v[0:1] op_sel_hi:[1,0]
	s_waitcnt lgkmcnt(0)
	v_pk_fma_f32 v[68:69], v[96:97], v[72:73], v[54:55]
	v_pk_fma_f32 v[70:71], v[168:169], v[70:71], v[52:53] neg_lo:[1,0,0] neg_hi:[1,0,0]
	v_pk_mul_f32 v[52:53], v[68:69], v[68:69]
	v_pk_mul_f32 v[54:55], v[70:71], v[70:71]
	v_pk_mul_f32 v[30:31], v[30:31], v[0:1] op_sel_hi:[1,0]
	v_pk_mov_b32 v[72:73], v[54:55], v[52:53] op_sel:[1,0]
	v_mov_b32_e32 v55, v53
	v_pk_add_f32 v[82:83], v[72:73], v[54:55]
	ds_read_b128 v[52:55], v190 offset:160
	v_pk_mul_f32 v[32:33], v[32:33], v[0:1] op_sel_hi:[1,0]
	s_lshl_b32 s36, s21, 1
	s_waitcnt lgkmcnt(0)
	v_pk_fma_f32 v[72:73], v[96:97], v[54:55], v[58:59]
	v_pk_fma_f32 v[74:75], v[168:169], v[52:53], v[56:57] neg_lo:[1,0,0] neg_hi:[1,0,0]
	ds_read_b128 v[54:57], v190 offset:192
	v_pk_mul_f32 v[58:59], v[60:61], v[0:1] op_sel_hi:[1,0]
	v_pk_mul_f32 v[52:53], v[62:63], v[0:1] op_sel_hi:[1,0]
	s_waitcnt lgkmcnt(0)
	v_pk_fma_f32 v[54:55], v[168:169], v[54:55], v[58:59] neg_lo:[1,0,0] neg_hi:[1,0,0]
	v_pk_fma_f32 v[52:53], v[96:97], v[56:57], v[52:53]
	v_mul_f32_e32 v58, v54, v54
	v_pk_add_f32 v[56:57], v[80:81], v[80:81] op_sel:[0,1] op_sel_hi:[1,0]
	v_mul_f32_e32 v60, v55, v55
	v_mov_b32_e32 v57, v58
	v_pk_add_f32 v[58:59], v[82:83], v[82:83] op_sel:[0,1] op_sel_hi:[1,0]
	v_mul_f32_e32 v61, v52, v52
	v_mov_b32_e32 v59, v60
	v_pk_add_f32 v[56:57], v[56:57], v[58:59]
	v_mul_f32_e32 v58, v75, v75
	v_pk_fma_f32 v[58:59], v[74:75], v[74:75], v[58:59] op_sel_hi:[1,1,0]
	v_mul_f32_e32 v60, v73, v73
	v_mul_f32_e32 v62, v53, v53
	v_mov_b32_e32 v59, v61
	v_pk_fma_f32 v[60:61], v[72:73], v[72:73], v[60:61] op_sel_hi:[1,1,0]
	s_nop 0
	v_mov_b32_e32 v61, v62
	v_pk_add_f32 v[58:59], v[58:59], v[60:61]
	v_pk_mul_f32 v[60:61], v[64:65], v[0:1] op_sel_hi:[1,0]
	v_pk_add_f32 v[80:81], v[56:57], v[58:59]
	ds_read_b128 v[56:59], v190 offset:224
	v_pk_mul_f32 v[62:63], v[66:67], v[0:1] op_sel_hi:[1,0]
	s_waitcnt lgkmcnt(0)
	v_pk_fma_f32 v[66:67], v[168:169], v[56:57], v[60:61] neg_lo:[1,0,0] neg_hi:[1,0,0]
	v_pk_fma_f32 v[64:65], v[96:97], v[58:59], v[62:63]
	v_pk_mul_f32 v[58:59], v[66:67], v[66:67]
	v_pk_mul_f32 v[56:57], v[64:65], v[64:65]
	s_nop 0
	v_pk_mov_b32 v[60:61], v[58:59], v[56:57] op_sel:[1,0]
	v_mov_b32_e32 v59, v57
	v_pk_add_f32 v[82:83], v[60:61], v[58:59]
	ds_read_b128 v[56:59], v190 offset:256
	s_waitcnt lgkmcnt(0)
	v_pk_fma_f32 v[60:61], v[96:97], v[58:59], v[38:39]
	v_pk_fma_f32 v[62:63], v[168:169], v[56:57], v[36:37] neg_lo:[1,0,0] neg_hi:[1,0,0]
	ds_read_b128 v[36:39], v190 offset:288
	s_waitcnt lgkmcnt(0)
; #define LAS __attribute__((address_space(3)))
; DI float shx(float v, int m, int lane) { return __builtin_bit_cast(float, __builtin_amdgcn_ds_bpermute((lane ^ m) << 2, __builtin_bit_cast(int, v))); }
; DI void attn_unit_d32(const Ctx& C, const bf16_t* __restrict__ Z, bf16_t* __restrict__ Y, int b, int qsel, int hsel, bool ctxq, float lam, float post_scale, const float* subln, const float mref) {
;     ...
;         f32x4 r[4][4]; float ss = 0.f;
; #pragma unroll
;         for (int d = 0; d < 4; ++d)
; #pragma unroll
;             for (int g = 0; g < 4; ++g) { const f32x4 x2 = *(const LAS f32x4*)(X + 32 * d + 8 * g + 4 * hh);
;                 const f32x4 x1 = {o[d][4 * g] * linv, o[d][4 * g + 1] * linv, o[d][4 * g + 2] * linv, o[d][4 * g + 3] * linv};
;                 r[d][g] = x1 - x2 * lam; ss += (r[d][g][0] * r[d][g][0] + r[d][g][1] * r[d][g][1]) + (r[d][g][2] * r[d][g][2] + r[d][g][3] * r[d][g][3]); }
;         ss += shx(ss, 32, lane);
	v_pk_fma_f32 v[58:59], v[168:169], v[36:37], v[40:41] neg_lo:[1,0,0] neg_hi:[1,0,0]
	v_pk_fma_f32 v[56:57], v[96:97], v[38:39], v[42:43]
	v_mul_f32_e32 v38, v58, v58
	v_pk_add_f32 v[36:37], v[80:81], v[80:81] op_sel:[0,1] op_sel_hi:[1,0]
	v_mul_f32_e32 v40, v59, v59
	v_mov_b32_e32 v37, v38
	v_pk_add_f32 v[38:39], v[82:83], v[82:83] op_sel:[0,1] op_sel_hi:[1,0]
	v_mul_f32_e32 v41, v56, v56
	v_mov_b32_e32 v39, v40
	v_pk_add_f32 v[36:37], v[36:37], v[38:39]
	v_mul_f32_e32 v38, v63, v63
	v_pk_fma_f32 v[38:39], v[62:63], v[62:63], v[38:39] op_sel_hi:[1,1,0]
	v_mul_f32_e32 v40, v61, v61
	v_mul_f32_e32 v42, v57, v57
	v_mov_b32_e32 v39, v41
	v_pk_fma_f32 v[40:41], v[60:61], v[60:61], v[40:41] op_sel_hi:[1,1,0]
	s_nop 0
	v_mov_b32_e32 v41, v42
	v_pk_add_f32 v[38:39], v[38:39], v[40:41]
	v_pk_mul_f32 v[42:43], v[44:45], v[0:1] op_sel_hi:[1,0]
	v_pk_add_f32 v[80:81], v[36:37], v[38:39]
	ds_read_b128 v[36:39], v190 offset:320
	v_pk_mul_f32 v[40:41], v[46:47], v[0:1] op_sel_hi:[1,0]
	s_waitcnt lgkmcnt(0)
	v_pk_fma_f32 v[42:43], v[168:169], v[36:37], v[42:43] neg_lo:[1,0,0] neg_hi:[1,0,0]
	v_pk_fma_f32 v[40:41], v[96:97], v[38:39], v[40:41]
	v_pk_mul_f32 v[38:39], v[42:43], v[42:43]
	v_pk_mul_f32 v[36:37], v[40:41], v[40:41]
	s_nop 0
	v_pk_mov_b32 v[44:45], v[38:39], v[36:37] op_sel:[1,0]
	v_mov_b32_e32 v39, v37
	v_pk_add_f32 v[82:83], v[44:45], v[38:39]
	ds_read_b128 v[44:47], v190 offset:352
	v_pk_mul_f32 v[38:39], v[48:49], v[0:1] op_sel_hi:[1,0]
	v_pk_mul_f32 v[36:37], v[50:51], v[0:1] op_sel_hi:[1,0]
	v_pk_mul_f32 v[48:49], v[20:21], v[0:1] op_sel_hi:[1,0]
	v_pk_mul_f32 v[20:21], v[22:23], v[0:1] op_sel_hi:[1,0]
	s_waitcnt lgkmcnt(0)
	v_pk_fma_f32 v[36:37], v[96:97], v[46:47], v[36:37]
	v_pk_fma_f32 v[38:39], v[168:169], v[44:45], v[38:39] neg_lo:[1,0,0] neg_hi:[1,0,0]
	ds_read_b128 v[44:47], v190 offset:384
	s_waitcnt lgkmcnt(0)
	v_pk_fma_f32 v[22:23], v[168:169], v[44:45], v[48:49] neg_lo:[1,0,0] neg_hi:[1,0,0]
	v_pk_fma_f32 v[20:21], v[96:97], v[46:47], v[20:21]
	v_mul_f32_e32 v46, v22, v22
	v_pk_add_f32 v[44:45], v[80:81], v[80:81] op_sel:[0,1] op_sel_hi:[1,0]
	v_mul_f32_e32 v48, v23, v23
	v_mov_b32_e32 v45, v46
	v_pk_add_f32 v[46:47], v[82:83], v[82:83] op_sel:[0,1] op_sel_hi:[1,0]
	v_mul_f32_e32 v49, v20, v20
	v_mov_b32_e32 v47, v48
	v_pk_add_f32 v[44:45], v[44:45], v[46:47]
	v_mul_f32_e32 v46, v39, v39
	v_pk_fma_f32 v[46:47], v[38:39], v[38:39], v[46:47] op_sel_hi:[1,1,0]
	v_mul_f32_e32 v48, v37, v37
	v_mul_f32_e32 v50, v21, v21
	v_mov_b32_e32 v47, v49
	v_pk_fma_f32 v[48:49], v[36:37], v[36:37], v[48:49] op_sel_hi:[1,1,0]
	s_nop 0
	v_mov_b32_e32 v49, v50
	v_pk_add_f32 v[46:47], v[46:47], v[48:49]
	s_nop 0
	v_pk_add_f32 v[50:51], v[44:45], v[46:47]
	ds_read_b128 v[44:47], v190 offset:416
	s_waitcnt lgkmcnt(0)
	v_pk_fma_f32 v[46:47], v[96:97], v[46:47], v[26:27]
	v_pk_fma_f32 v[48:49], v[168:169], v[44:45], v[24:25] neg_lo:[1,0,0] neg_hi:[1,0,0]
	v_pk_mul_f32 v[24:25], v[46:47], v[46:47]
	v_pk_mul_f32 v[26:27], v[48:49], v[48:49]
	s_nop 0
	v_pk_mov_b32 v[44:45], v[26:27], v[24:25] op_sel:[1,0]
	v_mov_b32_e32 v27, v25
	v_pk_add_f32 v[80:81], v[44:45], v[26:27]
	ds_read_b128 v[24:27], v190 offset:448
	s_waitcnt lgkmcnt(0)
	v_pk_fma_f32 v[30:31], v[96:97], v[26:27], v[30:31]
	v_pk_fma_f32 v[44:45], v[168:169], v[24:25], v[28:29] neg_lo:[1,0,0] neg_hi:[1,0,0]
	ds_read_b128 v[26:29], v190 offset:480
	v_pk_mul_f32 v[24:25], v[34:35], v[0:1] op_sel_hi:[1,0]
	s_waitcnt lgkmcnt(0)
	v_pk_fma_f32 v[26:27], v[168:169], v[26:27], v[32:33] neg_lo:[1,0,0] neg_hi:[1,0,0]
	v_pk_fma_f32 v[24:25], v[96:97], v[28:29], v[24:25]
	v_mul_f32_e32 v0, v26, v26
	v_mul_f32_e32 v34, v27, v27
	v_pk_add_f32 v[28:29], v[50:51], v[50:51] op_sel:[0,1] op_sel_hi:[1,0]
	v_pk_add_f32 v[32:33], v[80:81], v[80:81] op_sel:[0,1] op_sel_hi:[1,0]
	v_mov_b32_e32 v29, v0
	v_mov_b32_e32 v33, v34
	v_mul_f32_e32 v0, v45, v45
	v_mul_f32_e32 v35, v24, v24
	v_pk_add_f32 v[28:29], v[28:29], v[32:33]
	v_pk_fma_f32 v[32:33], v[44:45], v[44:45], v[0:1] op_sel_hi:[1,1,0]
	v_mul_f32_e32 v0, v31, v31
	v_mul_f32_e32 v82, v25, v25
	v_mov_b32_e32 v33, v35
	v_pk_fma_f32 v[34:35], v[30:31], v[30:31], v[0:1] op_sel_hi:[1,1,0]
	s_nop 0
	v_mov_b32_e32 v35, v82
	v_pk_add_f32 v[32:33], v[32:33], v[34:35]
	s_nop 0
	v_pk_add_f32 v[28:29], v[28:29], v[32:33]
	s_nop 0
	v_add_f32_e32 v0, v28, v29
	ds_bpermute_b32 v28, v186, v0
	s_waitcnt lgkmcnt(0)
; #define GAS __attribute__((address_space(1)))
; DI float shx(float v, int m, int lane) { return __builtin_bit_cast(float, __builtin_amdgcn_ds_bpermute((lane ^ m) << 2, __builtin_bit_cast(int, v))); }
; DI void attn_unit_d32(const Ctx& C, const bf16_t* __restrict__ Z, bf16_t* __restrict__ Y, int b, int qsel, int hsel, bool ctxq, float lam, float post_scale, const float* subln, const float mref) {
;     ...
;         ss += shx(ss, 32, lane);
;         const float rs = post_scale / sqrtf(ss * (1.f / 128.f) + EPS);
;         bf16_t* yp = Y + (size_t)qrow * DM + ycol;
; #pragma unroll
;         for (int d = 0; d < 4; ++d)
; #pragma unroll
;             for (int g = 0; g < 4; ++g) { const int dv = 32 * d + 8 * g + 4 * hh; const f32x4 gn = *(const GAS f32x4*)(subln + dv); const f32x4 v = r[d][g] * rs * gn;
	v_add_f32_e32 v0, v0, v28
	v_fmamk_f32 v0, v0, 0x3c000000, v227
	v_cmp_gt_f32_e32 vcc, s67, v0
	v_mul_f32_e32 v28, 0x4f800000, v0
	s_nop 0
	v_cndmask_b32_e32 v0, v0, v28, vcc
	v_sqrt_f32_e32 v28, v0
	s_nop 0
	v_add_u32_e32 v29, -1, v28
	v_fma_f32 v32, -v29, v28, v0
	v_cmp_ge_f32_e64 s[0:1], 0, v32
	v_add_u32_e32 v32, 1, v28
	s_nop 0
	v_cndmask_b32_e64 v29, v28, v29, s[0:1]
	v_fma_f32 v28, -v32, v28, v0
	v_cmp_lt_f32_e64 s[0:1], 0, v28
	s_nop 1
	v_cndmask_b32_e64 v28, v29, v32, s[0:1]
	v_mul_f32_e32 v29, 0x37800000, v28
	v_cndmask_b32_e32 v28, v28, v29, vcc
	v_cmp_class_f32_e32 vcc, v0, v228
	s_nop 1
	v_cndmask_b32_e32 v0, v28, v0, vcc
	v_div_scale_f32 v28, s[0:1], v0, v0, v176
	v_rcp_f32_e32 v29, v28
	s_nop 0
	v_fma_f32 v32, -v28, v29, 1.0
	v_fmac_f32_e32 v29, v32, v29
	v_div_scale_f32 v32, vcc, v176, v0, v176
	v_mul_f32_e32 v33, v32, v29
	v_fma_f32 v34, -v28, v33, v32
	v_fmac_f32_e32 v33, v34, v29
	v_fma_f32 v28, -v28, v33, v32
	v_div_fmas_f32 v28, v28, v29, v33
	global_load_dwordx4 v[140:143], v[170:171], off
	global_load_dwordx4 v[144:147], v[170:171], off offset:32
	global_load_dwordx4 v[148:151], v[170:171], off offset:64
	global_load_dwordx4 v[152:155], v[170:171], off offset:96
	global_load_dwordx4 v[158:161], v[170:171], off offset:128
	global_load_dwordx4 v[192:195], v[170:171], off offset:160
	global_load_dwordx4 v[202:205], v[170:171], off offset:192
	global_load_dwordx4 v[210:213], v[170:171], off offset:224
	global_load_dwordx4 v[214:217], v[170:171], off offset:256
	global_load_dwordx4 v[218:221], v[170:171], off offset:288
	global_load_dwordx4 v[222:225], v[170:171], off offset:320
	global_load_dwordx4 v[240:243], v[170:171], off offset:352
	global_load_dwordx4 v[244:247], v[170:171], off offset:384
	v_div_fixup_f32 v0, v28, v0, v176
	v_lshlrev_b64 v[28:29], 12, v[172:173]
	v_lshl_add_u64 v[28:29], s[10:11], 0, v[28:29]
	v_pk_mul_f32 v[50:51], v[94:95], v[0:1] op_sel_hi:[1,0]
	v_pk_mul_f32 v[80:81], v[92:93], v[0:1] op_sel_hi:[1,0]
	v_lshl_add_u64 v[28:29], v[28:29], 0, s[36:37]
	v_lshl_add_u64 v[28:29], v[166:167], 1, v[28:29]
	v_pk_mul_f32 v[76:77], v[76:77], v[0:1] op_sel_hi:[1,0]
	v_pk_mul_f32 v[68:69], v[68:69], v[0:1] op_sel_hi:[1,0]
	v_pk_mul_f32 v[52:53], v[52:53], v[0:1] op_sel_hi:[1,0]
	v_pk_mul_f32 v[42:43], v[42:43], v[0:1] op_sel_hi:[1,0]
	v_pk_mul_f32 v[40:41], v[40:41], v[0:1] op_sel_hi:[1,0]
	v_pk_mul_f32 v[38:39], v[38:39], v[0:1] op_sel_hi:[1,0]
	v_pk_mul_f32 v[36:37], v[36:37], v[0:1] op_sel_hi:[1,0]
	v_pk_mul_f32 v[22:23], v[22:23], v[0:1] op_sel_hi:[1,0]
	v_pk_mul_f32 v[20:21], v[20:21], v[0:1] op_sel_hi:[1,0]
	v_pk_mul_f32 v[30:31], v[30:31], v[0:1] op_sel_hi:[1,0]
	v_pk_mul_f32 v[26:27], v[26:27], v[0:1] op_sel_hi:[1,0]
	v_pk_mul_f32 v[24:25], v[24:25], v[0:1] op_sel_hi:[1,0]
	s_waitcnt vmcnt(0)
; #define GAS __attribute__((address_space(1)))
; DI unsigned pk2(float lo, float hi) { f32x2 v = {lo, hi}; bf16x2_t b = __builtin_convertvector(v, bf16x2_t); return __builtin_bit_cast(unsigned, b); }
; DI void attn_unit_d32(const Ctx& C, const bf16_t* __restrict__ Z, bf16_t* __restrict__ Y, int b, int qsel, int hsel, bool ctxq, float lam, float post_scale, const float* subln, const float mref) {
;     ...
;         bf16_t* yp = Y + (size_t)qrow * DM + ycol;
; #pragma unroll
;         for (int d = 0; d < 4; ++d)
; #pragma unroll
;             for (int g = 0; g < 4; ++g) { const int dv = 32 * d + 8 * g + 4 * hh; const f32x4 gn = *(const GAS f32x4*)(subln + dv); const f32x4 v = r[d][g] * rs * gn;
;                 u32x2 wv; wv.x = pk2(v[0], v[1]); wv.y = pk2(v[2], v[3]); *(GAS u32x2*)(yp + dv) = wv; }
	v_pk_mul_f32 v[34:35], v[142:143], v[80:81]
	v_pk_mul_f32 v[32:33], v[140:141], v[50:51]
	v_pk_mul_f32 v[50:51], v[90:91], v[0:1] op_sel_hi:[1,0]
	v_cvt_pk_bf16_f32 v32, v32, v33
	v_cvt_pk_bf16_f32 v33, v34, v35
	global_store_dwordx2 v[28:29], v[32:33], off offset:3072
	v_pk_mul_f32 v[80:81], v[88:89], v[0:1] op_sel_hi:[1,0]
	v_pk_mul_f32 v[32:33], v[144:145], v[50:51]
	v_pk_mul_f32 v[34:35], v[146:147], v[80:81]
	v_cvt_pk_bf16_f32 v32, v32, v33
	v_cvt_pk_bf16_f32 v33, v34, v35
	global_store_dwordx2 v[28:29], v[32:33], off offset:3088
	v_pk_mul_f32 v[50:51], v[86:87], v[0:1] op_sel_hi:[1,0]
	v_pk_mul_f32 v[80:81], v[84:85], v[0:1] op_sel_hi:[1,0]
	v_pk_mul_f32 v[32:33], v[148:149], v[50:51]
	v_pk_mul_f32 v[34:35], v[150:151], v[80:81]
	v_cvt_pk_bf16_f32 v32, v32, v33
	v_cvt_pk_bf16_f32 v33, v34, v35
	global_store_dwordx2 v[28:29], v[32:33], off offset:3104
	global_load_dwordx4 v[140:143], v[170:171], off offset:416
	global_load_dwordx4 v[144:147], v[170:171], off offset:448
	global_load_dwordx4 v[148:151], v[170:171], off offset:480
	v_pk_mul_f32 v[50:51], v[78:79], v[0:1] op_sel_hi:[1,0]
	v_pk_mul_f32 v[34:35], v[154:155], v[76:77]
	v_pk_mul_f32 v[32:33], v[152:153], v[50:51]
	v_pk_mul_f32 v[50:51], v[70:71], v[0:1] op_sel_hi:[1,0]
	v_cvt_pk_bf16_f32 v32, v32, v33
	v_cvt_pk_bf16_f32 v33, v34, v35
	global_store_dwordx2 v[28:29], v[32:33], off offset:3120
	v_pk_mul_f32 v[34:35], v[160:161], v[68:69]
	v_pk_mul_f32 v[32:33], v[158:159], v[50:51]
	v_pk_mul_f32 v[50:51], v[74:75], v[0:1] op_sel_hi:[1,0]
	v_cvt_pk_bf16_f32 v32, v32, v33
	v_cvt_pk_bf16_f32 v33, v34, v35
	global_store_dwordx2 v[28:29], v[32:33], off offset:3136
	v_pk_mul_f32 v[68:69], v[72:73], v[0:1] op_sel_hi:[1,0]
	v_pk_mul_f32 v[32:33], v[192:193], v[50:51]
	v_pk_mul_f32 v[34:35], v[194:195], v[68:69]
	v_cvt_pk_bf16_f32 v32, v32, v33
	v_cvt_pk_bf16_f32 v33, v34, v35
	global_store_dwordx2 v[28:29], v[32:33], off offset:3152
	v_pk_mul_f32 v[50:51], v[54:55], v[0:1] op_sel_hi:[1,0]
	v_pk_mul_f32 v[34:35], v[204:205], v[52:53]
	v_pk_mul_f32 v[32:33], v[202:203], v[50:51]
	v_pk_mul_f32 v[50:51], v[66:67], v[0:1] op_sel_hi:[1,0]
	v_cvt_pk_bf16_f32 v32, v32, v33
	v_cvt_pk_bf16_f32 v33, v34, v35
	global_store_dwordx2 v[28:29], v[32:33], off offset:3168
	v_pk_mul_f32 v[52:53], v[64:65], v[0:1] op_sel_hi:[1,0]
	v_pk_mul_f32 v[32:33], v[50:51], v[210:211]
	v_pk_mul_f32 v[34:35], v[52:53], v[212:213]
	v_cvt_pk_bf16_f32 v32, v32, v33
	v_cvt_pk_bf16_f32 v33, v34, v35
	global_store_dwordx2 v[28:29], v[32:33], off offset:3184
	v_pk_mul_f32 v[50:51], v[62:63], v[0:1] op_sel_hi:[1,0]
	v_pk_mul_f32 v[52:53], v[60:61], v[0:1] op_sel_hi:[1,0]
	v_pk_mul_f32 v[32:33], v[50:51], v[214:215]
	v_pk_mul_f32 v[34:35], v[52:53], v[216:217]
	v_cvt_pk_bf16_f32 v32, v32, v33
	v_cvt_pk_bf16_f32 v33, v34, v35
	global_store_dwordx2 v[28:29], v[32:33], off offset:3200
	v_pk_mul_f32 v[50:51], v[58:59], v[0:1] op_sel_hi:[1,0]
	v_pk_mul_f32 v[52:53], v[56:57], v[0:1] op_sel_hi:[1,0]
	v_pk_mul_f32 v[32:33], v[50:51], v[218:219]
	v_pk_mul_f32 v[34:35], v[52:53], v[220:221]
	v_cvt_pk_bf16_f32 v32, v32, v33
	v_cvt_pk_bf16_f32 v33, v34, v35
	global_store_dwordx2 v[28:29], v[32:33], off offset:3216
	v_pk_mul_f32 v[34:35], v[40:41], v[224:225]
	v_pk_mul_f32 v[32:33], v[42:43], v[222:223]
	s_nop 0
	v_cvt_pk_bf16_f32 v32, v32, v33
	v_cvt_pk_bf16_f32 v33, v34, v35
	global_store_dwordx2 v[28:29], v[32:33], off offset:3232
	v_pk_mul_f32 v[34:35], v[36:37], v[242:243]
	v_pk_mul_f32 v[32:33], v[38:39], v[240:241]
	s_nop 0
	v_cvt_pk_bf16_f32 v32, v32, v33
	v_cvt_pk_bf16_f32 v33, v34, v35
	global_store_dwordx2 v[28:29], v[32:33], off offset:3248
	v_pk_mul_f32 v[20:21], v[20:21], v[246:247]
	v_pk_mul_f32 v[22:23], v[22:23], v[244:245]
	v_pk_mul_f32 v[32:33], v[48:49], v[0:1] op_sel_hi:[1,0]
	v_cvt_pk_bf16_f32 v22, v22, v23
	v_cvt_pk_bf16_f32 v23, v20, v21
	global_store_dwordx2 v[28:29], v[22:23], off offset:3264
	s_waitcnt vmcnt(10)
	v_pk_mul_f32 v[34:35], v[46:47], v[0:1] op_sel_hi:[1,0]
	v_pk_mul_f32 v[20:21], v[32:33], v[140:141]
	v_pk_mul_f32 v[22:23], v[34:35], v[142:143]
	v_cvt_pk_bf16_f32 v20, v20, v21
	v_cvt_pk_bf16_f32 v21, v22, v23
	global_store_dwordx2 v[28:29], v[20:21], off offset:3280
	v_pk_mul_f32 v[32:33], v[44:45], v[0:1] op_sel_hi:[1,0]
	v_pk_mul_f32 v[22:23], v[30:31], v[146:147]
	v_pk_mul_f32 v[20:21], v[32:33], v[144:145]
	s_nop 0
	v_cvt_pk_bf16_f32 v20, v20, v21
	v_cvt_pk_bf16_f32 v21, v22, v23
	global_store_dwordx2 v[28:29], v[20:21], off offset:3296
	v_pk_mul_f32 v[22:23], v[24:25], v[150:151]
	v_pk_mul_f32 v[20:21], v[26:27], v[148:149]
	s_nop 0
	v_cvt_pk_bf16_f32 v20, v20, v21
	v_cvt_pk_bf16_f32 v21, v22, v23
	global_store_dwordx2 v[28:29], v[20:21], off offset:3312
	s_branch .LBB0_396

; #define LAS __attribute__((address_space(3)))
; DI void attn_unit_d32(const Ctx& C, const bf16_t* __restrict__ Z, bf16_t* __restrict__ Y, int b, int qsel, int hsel, bool ctxq, float lam, float post_scale, const float* subln, const float mref) {
;     ...
;     __syncthreads();
;     if (sm == 0) {
;         f32x4 r[4][4]; float ss = 0.f;
; #pragma unroll
;         for (int d = 0; d < 4; ++d)
; #pragma unroll
;             for (int g = 0; g < 4; ++g) { const f32x4 x2 = *(const LAS f32x4*)(X + 32 * d + 8 * g + 4 * hh);
;                 const f32x4 x1 = {o[d][4 * g] * linv, o[d][4 * g + 1] * linv, o[d][4 * g + 2] * linv, o[d][4 * g + 3] * linv};
;                 r[d][g] = x1 - x2 * lam; ss += (r[d][g][0] * r[d][g][0] + r[d][g][1] * r[d][g][1]) + (r[d][g][2] * r[d][g][2] + r[d][g][3] * r[d][g][3]); }
.LBB0_546:
	s_andn2_b64 vcc, exec, s[6:7]
	s_waitcnt lgkmcnt(0)
	s_barrier
	s_cbranch_vccnz .LBB0_541
	ds_read_b128 v[84:87], v163
	ds_read_b128 v[98:101], v163 offset:32
	v_xor_b32_e32 v96, 0x80000000, v168
	v_pk_mul_f32 v[68:69], v[68:69], v[0:1] op_sel_hi:[1,0]
	v_pk_mul_f32 v[70:71], v[70:71], v[0:1] op_sel_hi:[1,0]
	v_mov_b32_e32 v97, v96
	s_waitcnt lgkmcnt(1)
	v_pk_fma_f32 v[92:93], v[96:97], v[86:87], v[70:71]
	v_pk_fma_f32 v[94:95], v[168:169], v[84:85], v[68:69] neg_lo:[1,0,0] neg_hi:[1,0,0]
	v_pk_mul_f32 v[68:69], v[92:93], v[92:93]
	v_pk_mul_f32 v[70:71], v[94:95], v[94:95]
	v_pk_mul_f32 v[52:53], v[52:53], v[0:1] op_sel_hi:[1,0]
	v_pk_mov_b32 v[84:85], v[70:71], v[68:69] op_sel:[1,0]
	v_mov_b32_e32 v71, v69
	v_pk_add_f32 v[102:103], v[84:85], v[70:71]
	v_pk_mul_f32 v[68:69], v[72:73], v[0:1] op_sel_hi:[1,0]
	v_pk_mul_f32 v[70:71], v[74:75], v[0:1] op_sel_hi:[1,0]
	s_waitcnt lgkmcnt(0)
	v_pk_fma_f32 v[90:91], v[168:169], v[98:99], v[68:69] neg_lo:[1,0,0] neg_hi:[1,0,0]
	v_pk_fma_f32 v[88:89], v[96:97], v[100:101], v[70:71]
	v_pk_mul_f32 v[70:71], v[90:91], v[90:91]
	v_pk_mul_f32 v[68:69], v[88:89], v[88:89]
	v_pk_mul_f32 v[74:75], v[76:77], v[0:1] op_sel_hi:[1,0]
	v_pk_mov_b32 v[72:73], v[70:71], v[68:69] op_sel:[1,0]
	v_mov_b32_e32 v71, v69
	v_pk_add_f32 v[72:73], v[72:73], v[70:71]
	ds_read_b128 v[68:71], v163 offset:64
	v_pk_mul_f32 v[76:77], v[78:79], v[0:1] op_sel_hi:[1,0]
	v_pk_mul_f32 v[54:55], v[54:55], v[0:1] op_sel_hi:[1,0]
	v_pk_mul_f32 v[56:57], v[56:57], v[0:1] op_sel_hi:[1,0]
	v_pk_mul_f32 v[58:59], v[58:59], v[0:1] op_sel_hi:[1,0]
	s_waitcnt lgkmcnt(0)
	v_pk_fma_f32 v[84:85], v[96:97], v[70:71], v[76:77]
	v_pk_fma_f32 v[86:87], v[168:169], v[68:69], v[74:75] neg_lo:[1,0,0] neg_hi:[1,0,0]
	ds_read_b128 v[68:71], v163 offset:96
	v_pk_mul_f32 v[74:75], v[80:81], v[0:1] op_sel_hi:[1,0]
	v_pk_mul_f32 v[76:77], v[82:83], v[0:1] op_sel_hi:[1,0]
	v_pk_mul_f32 v[36:37], v[36:37], v[0:1] op_sel_hi:[1,0]
	v_pk_mul_f32 v[38:39], v[38:39], v[0:1] op_sel_hi:[1,0]
	s_waitcnt lgkmcnt(0)
	v_pk_fma_f32 v[78:79], v[168:169], v[68:69], v[74:75] neg_lo:[1,0,0] neg_hi:[1,0,0]
	v_pk_fma_f32 v[76:77], v[96:97], v[70:71], v[76:77]
	v_mul_f32_e32 v70, v78, v78
	v_pk_add_f32 v[68:69], v[102:103], v[102:103] op_sel:[0,1] op_sel_hi:[1,0]
	v_mul_f32_e32 v74, v79, v79
	v_mov_b32_e32 v69, v70
	v_pk_add_f32 v[70:71], v[72:73], v[72:73] op_sel:[0,1] op_sel_hi:[1,0]
	v_mul_f32_e32 v72, v85, v85
	v_mov_b32_e32 v71, v74
	v_pk_add_f32 v[68:69], v[68:69], v[70:71]
	v_mul_f32_e32 v70, v87, v87
	v_mul_f32_e32 v75, v76, v76
	v_mul_f32_e32 v80, v77, v77
	v_pk_fma_f32 v[70:71], v[86:87], v[86:87], v[70:71] op_sel_hi:[1,1,0]
	v_pk_fma_f32 v[72:73], v[84:85], v[84:85], v[72:73] op_sel_hi:[1,1,0]
	v_mov_b32_e32 v71, v75
	v_mov_b32_e32 v73, v80
	v_pk_add_f32 v[70:71], v[70:71], v[72:73]
	v_pk_mul_f32 v[40:41], v[40:41], v[0:1] op_sel_hi:[1,0]
	v_pk_add_f32 v[80:81], v[68:69], v[70:71]
	ds_read_b128 v[70:73], v163 offset:128
	v_pk_mul_f32 v[42:43], v[42:43], v[0:1] op_sel_hi:[1,0]
	v_pk_mul_f32 v[24:25], v[24:25], v[0:1] op_sel_hi:[1,0]
	v_pk_mul_f32 v[26:27], v[26:27], v[0:1] op_sel_hi:[1,0]
	v_pk_mul_f32 v[28:29], v[28:29], v[0:1] op_sel_hi:[1,0]
	s_waitcnt lgkmcnt(0)
	v_pk_fma_f32 v[68:69], v[96:97], v[72:73], v[54:55]
	v_pk_fma_f32 v[70:71], v[168:169], v[70:71], v[52:53] neg_lo:[1,0,0] neg_hi:[1,0,0]
	v_pk_mul_f32 v[52:53], v[68:69], v[68:69]
	v_pk_mul_f32 v[54:55], v[70:71], v[70:71]
	v_pk_mul_f32 v[30:31], v[30:31], v[0:1] op_sel_hi:[1,0]
	v_pk_mov_b32 v[72:73], v[54:55], v[52:53] op_sel:[1,0]
	v_mov_b32_e32 v55, v53
	v_pk_add_f32 v[82:83], v[72:73], v[54:55]
	ds_read_b128 v[52:55], v163 offset:160
	v_pk_mul_f32 v[32:33], v[32:33], v[0:1] op_sel_hi:[1,0]
	v_mov_b32_e32 v153, v1
	s_lshl_b32 s36, s18, 1
	s_waitcnt lgkmcnt(0)
	v_pk_fma_f32 v[72:73], v[96:97], v[54:55], v[58:59]
	v_pk_fma_f32 v[74:75], v[168:169], v[52:53], v[56:57] neg_lo:[1,0,0] neg_hi:[1,0,0]
	ds_read_b128 v[54:57], v163 offset:192
	v_pk_mul_f32 v[58:59], v[60:61], v[0:1] op_sel_hi:[1,0]
	v_pk_mul_f32 v[52:53], v[62:63], v[0:1] op_sel_hi:[1,0]
	s_waitcnt lgkmcnt(0)
	v_pk_fma_f32 v[54:55], v[168:169], v[54:55], v[58:59] neg_lo:[1,0,0] neg_hi:[1,0,0]
	v_pk_fma_f32 v[52:53], v[96:97], v[56:57], v[52:53]
	v_mul_f32_e32 v58, v54, v54
	v_pk_add_f32 v[56:57], v[80:81], v[80:81] op_sel:[0,1] op_sel_hi:[1,0]
	v_mul_f32_e32 v60, v55, v55
	v_mov_b32_e32 v57, v58
	v_pk_add_f32 v[58:59], v[82:83], v[82:83] op_sel:[0,1] op_sel_hi:[1,0]
	v_mul_f32_e32 v61, v52, v52
	v_mov_b32_e32 v59, v60
	v_pk_add_f32 v[56:57], v[56:57], v[58:59]
	v_mul_f32_e32 v58, v75, v75
	v_pk_fma_f32 v[58:59], v[74:75], v[74:75], v[58:59] op_sel_hi:[1,1,0]
	v_mul_f32_e32 v60, v73, v73
	v_mul_f32_e32 v62, v53, v53
	v_mov_b32_e32 v59, v61
	v_pk_fma_f32 v[60:61], v[72:73], v[72:73], v[60:61] op_sel_hi:[1,1,0]
	s_nop 0
	v_mov_b32_e32 v61, v62
	v_pk_add_f32 v[58:59], v[58:59], v[60:61]
	v_pk_mul_f32 v[60:61], v[64:65], v[0:1] op_sel_hi:[1,0]
	v_pk_add_f32 v[80:81], v[56:57], v[58:59]
	ds_read_b128 v[56:59], v163 offset:224
	v_pk_mul_f32 v[62:63], v[66:67], v[0:1] op_sel_hi:[1,0]
	s_waitcnt lgkmcnt(0)
	v_pk_fma_f32 v[66:67], v[168:169], v[56:57], v[60:61] neg_lo:[1,0,0] neg_hi:[1,0,0]
	v_pk_fma_f32 v[64:65], v[96:97], v[58:59], v[62:63]
	v_pk_mul_f32 v[58:59], v[66:67], v[66:67]
	v_pk_mul_f32 v[56:57], v[64:65], v[64:65]
	s_nop 0
	v_pk_mov_b32 v[60:61], v[58:59], v[56:57] op_sel:[1,0]
	v_mov_b32_e32 v59, v57
	v_pk_add_f32 v[82:83], v[60:61], v[58:59]
	ds_read_b128 v[56:59], v163 offset:256
	s_waitcnt lgkmcnt(0)
	v_pk_fma_f32 v[60:61], v[96:97], v[58:59], v[38:39]
	v_pk_fma_f32 v[62:63], v[168:169], v[56:57], v[36:37] neg_lo:[1,0,0] neg_hi:[1,0,0]
	ds_read_b128 v[36:39], v163 offset:288
	s_waitcnt lgkmcnt(0)
; #define LAS __attribute__((address_space(3)))
; DI float shx(float v, int m, int lane) { return __builtin_bit_cast(float, __builtin_amdgcn_ds_bpermute((lane ^ m) << 2, __builtin_bit_cast(int, v))); }
; DI void attn_unit_d32(const Ctx& C, const bf16_t* __restrict__ Z, bf16_t* __restrict__ Y, int b, int qsel, int hsel, bool ctxq, float lam, float post_scale, const float* subln, const float mref) {
;     ...
;         f32x4 r[4][4]; float ss = 0.f;
; #pragma unroll
;         for (int d = 0; d < 4; ++d)
; #pragma unroll
;             for (int g = 0; g < 4; ++g) { const f32x4 x2 = *(const LAS f32x4*)(X + 32 * d + 8 * g + 4 * hh);
;                 const f32x4 x1 = {o[d][4 * g] * linv, o[d][4 * g + 1] * linv, o[d][4 * g + 2] * linv, o[d][4 * g + 3] * linv};
;                 r[d][g] = x1 - x2 * lam; ss += (r[d][g][0] * r[d][g][0] + r[d][g][1] * r[d][g][1]) + (r[d][g][2] * r[d][g][2] + r[d][g][3] * r[d][g][3]); }
;         ss += shx(ss, 32, lane);
	v_pk_fma_f32 v[58:59], v[168:169], v[36:37], v[40:41] neg_lo:[1,0,0] neg_hi:[1,0,0]
	v_pk_fma_f32 v[56:57], v[96:97], v[38:39], v[42:43]
	v_mul_f32_e32 v38, v58, v58
	v_pk_add_f32 v[36:37], v[80:81], v[80:81] op_sel:[0,1] op_sel_hi:[1,0]
	v_mul_f32_e32 v40, v59, v59
	v_mov_b32_e32 v37, v38
	v_pk_add_f32 v[38:39], v[82:83], v[82:83] op_sel:[0,1] op_sel_hi:[1,0]
	v_mul_f32_e32 v41, v56, v56
	v_mov_b32_e32 v39, v40
	v_pk_add_f32 v[36:37], v[36:37], v[38:39]
	v_mul_f32_e32 v38, v63, v63
	v_pk_fma_f32 v[38:39], v[62:63], v[62:63], v[38:39] op_sel_hi:[1,1,0]
	v_mul_f32_e32 v40, v61, v61
	v_mul_f32_e32 v42, v57, v57
	v_mov_b32_e32 v39, v41
	v_pk_fma_f32 v[40:41], v[60:61], v[60:61], v[40:41] op_sel_hi:[1,1,0]
	s_nop 0
	v_mov_b32_e32 v41, v42
	v_pk_add_f32 v[38:39], v[38:39], v[40:41]
	v_pk_mul_f32 v[42:43], v[44:45], v[0:1] op_sel_hi:[1,0]
	v_pk_add_f32 v[80:81], v[36:37], v[38:39]
	ds_read_b128 v[36:39], v163 offset:320
	v_pk_mul_f32 v[40:41], v[46:47], v[0:1] op_sel_hi:[1,0]
	s_waitcnt lgkmcnt(0)
	v_pk_fma_f32 v[42:43], v[168:169], v[36:37], v[42:43] neg_lo:[1,0,0] neg_hi:[1,0,0]
	v_pk_fma_f32 v[40:41], v[96:97], v[38:39], v[40:41]
	v_pk_mul_f32 v[38:39], v[42:43], v[42:43]
	v_pk_mul_f32 v[36:37], v[40:41], v[40:41]
	s_nop 0
	v_pk_mov_b32 v[44:45], v[38:39], v[36:37] op_sel:[1,0]
	v_mov_b32_e32 v39, v37
	v_pk_add_f32 v[82:83], v[44:45], v[38:39]
	ds_read_b128 v[44:47], v163 offset:352
	v_pk_mul_f32 v[38:39], v[48:49], v[0:1] op_sel_hi:[1,0]
	v_pk_mul_f32 v[36:37], v[50:51], v[0:1] op_sel_hi:[1,0]
	v_pk_mul_f32 v[48:49], v[20:21], v[0:1] op_sel_hi:[1,0]
	v_pk_mul_f32 v[20:21], v[22:23], v[0:1] op_sel_hi:[1,0]
	s_waitcnt lgkmcnt(0)
	v_pk_fma_f32 v[36:37], v[96:97], v[46:47], v[36:37]
	v_pk_fma_f32 v[38:39], v[168:169], v[44:45], v[38:39] neg_lo:[1,0,0] neg_hi:[1,0,0]
	ds_read_b128 v[44:47], v163 offset:384
	s_waitcnt lgkmcnt(0)
	v_pk_fma_f32 v[22:23], v[168:169], v[44:45], v[48:49] neg_lo:[1,0,0] neg_hi:[1,0,0]
	v_pk_fma_f32 v[20:21], v[96:97], v[46:47], v[20:21]
	v_mul_f32_e32 v46, v22, v22
	v_pk_add_f32 v[44:45], v[80:81], v[80:81] op_sel:[0,1] op_sel_hi:[1,0]
	v_mul_f32_e32 v48, v23, v23
	v_mov_b32_e32 v45, v46
	v_pk_add_f32 v[46:47], v[82:83], v[82:83] op_sel:[0,1] op_sel_hi:[1,0]
	v_mul_f32_e32 v49, v20, v20
	v_mov_b32_e32 v47, v48
	v_pk_add_f32 v[44:45], v[44:45], v[46:47]
	v_mul_f32_e32 v46, v39, v39
	v_pk_fma_f32 v[46:47], v[38:39], v[38:39], v[46:47] op_sel_hi:[1,1,0]
	v_mul_f32_e32 v48, v37, v37
	v_mul_f32_e32 v50, v21, v21
	v_mov_b32_e32 v47, v49
	v_pk_fma_f32 v[48:49], v[36:37], v[36:37], v[48:49] op_sel_hi:[1,1,0]
	s_nop 0
	v_mov_b32_e32 v49, v50
	v_pk_add_f32 v[46:47], v[46:47], v[48:49]
	s_nop 0
	v_pk_add_f32 v[50:51], v[44:45], v[46:47]
	ds_read_b128 v[44:47], v163 offset:416
	s_waitcnt lgkmcnt(0)
	v_pk_fma_f32 v[46:47], v[96:97], v[46:47], v[26:27]
	v_pk_fma_f32 v[48:49], v[168:169], v[44:45], v[24:25] neg_lo:[1,0,0] neg_hi:[1,0,0]
	v_pk_mul_f32 v[24:25], v[46:47], v[46:47]
	v_pk_mul_f32 v[26:27], v[48:49], v[48:49]
	s_nop 0
	v_pk_mov_b32 v[44:45], v[26:27], v[24:25] op_sel:[1,0]
	v_mov_b32_e32 v27, v25
	v_pk_add_f32 v[80:81], v[44:45], v[26:27]
	ds_read_b128 v[24:27], v163 offset:448
	s_waitcnt lgkmcnt(0)
	v_pk_fma_f32 v[30:31], v[96:97], v[26:27], v[30:31]
	v_pk_fma_f32 v[44:45], v[168:169], v[24:25], v[28:29] neg_lo:[1,0,0] neg_hi:[1,0,0]
	ds_read_b128 v[26:29], v163 offset:480
	v_pk_mul_f32 v[24:25], v[34:35], v[0:1] op_sel_hi:[1,0]
	s_waitcnt lgkmcnt(0)
	v_pk_fma_f32 v[26:27], v[168:169], v[26:27], v[32:33] neg_lo:[1,0,0] neg_hi:[1,0,0]
	v_pk_fma_f32 v[24:25], v[96:97], v[28:29], v[24:25]
	v_mul_f32_e32 v0, v26, v26
	v_mul_f32_e32 v34, v27, v27
	v_pk_add_f32 v[28:29], v[50:51], v[50:51] op_sel:[0,1] op_sel_hi:[1,0]
	v_pk_add_f32 v[32:33], v[80:81], v[80:81] op_sel:[0,1] op_sel_hi:[1,0]
	v_mov_b32_e32 v29, v0
	v_mov_b32_e32 v33, v34
	v_mul_f32_e32 v0, v45, v45
	v_mul_f32_e32 v35, v24, v24
	v_pk_add_f32 v[28:29], v[28:29], v[32:33]
	v_pk_fma_f32 v[32:33], v[44:45], v[44:45], v[0:1] op_sel_hi:[1,1,0]
	v_mul_f32_e32 v0, v31, v31
	v_mul_f32_e32 v82, v25, v25
	v_mov_b32_e32 v33, v35
	v_pk_fma_f32 v[34:35], v[30:31], v[30:31], v[0:1] op_sel_hi:[1,1,0]
	s_nop 0
	v_mov_b32_e32 v35, v82
	v_pk_add_f32 v[32:33], v[32:33], v[34:35]
	s_nop 0
	v_pk_add_f32 v[28:29], v[28:29], v[32:33]
	s_nop 0
	v_add_f32_e32 v0, v28, v29
	ds_bpermute_b32 v28, v158, v0
	s_waitcnt lgkmcnt(0)
; #define GAS __attribute__((address_space(1)))
; DI float shx(float v, int m, int lane) { return __builtin_bit_cast(float, __builtin_amdgcn_ds_bpermute((lane ^ m) << 2, __builtin_bit_cast(int, v))); }
; DI void attn_unit_d32(const Ctx& C, const bf16_t* __restrict__ Z, bf16_t* __restrict__ Y, int b, int qsel, int hsel, bool ctxq, float lam, float post_scale, const float* subln, const float mref) {
;     ...
;         ss += shx(ss, 32, lane);
;         const float rs = post_scale / sqrtf(ss * (1.f / 128.f) + EPS);
;         bf16_t* yp = Y + (size_t)qrow * DM + ycol;
; #pragma unroll
;         for (int d = 0; d < 4; ++d)
; #pragma unroll
;             for (int g = 0; g < 4; ++g) { const int dv = 32 * d + 8 * g + 4 * hh; const f32x4 gn = *(const GAS f32x4*)(subln + dv); const f32x4 v = r[d][g] * rs * gn;
	v_add_f32_e32 v0, v0, v28
	v_fmamk_f32 v0, v0, 0x3c000000, v227
	v_cmp_gt_f32_e32 vcc, s67, v0
	v_mul_f32_e32 v28, 0x4f800000, v0
	s_nop 0
	v_cndmask_b32_e32 v0, v0, v28, vcc
	v_sqrt_f32_e32 v28, v0
	s_nop 0
	v_add_u32_e32 v29, -1, v28
	v_fma_f32 v32, -v29, v28, v0
	v_cmp_ge_f32_e64 s[0:1], 0, v32
	v_add_u32_e32 v32, 1, v28
	s_nop 0
	v_cndmask_b32_e64 v29, v28, v29, s[0:1]
	v_fma_f32 v28, -v32, v28, v0
	v_cmp_lt_f32_e64 s[0:1], 0, v28
	s_nop 1
	v_cndmask_b32_e64 v28, v29, v32, s[0:1]
	v_mul_f32_e32 v29, 0x37800000, v28
	v_cndmask_b32_e32 v28, v28, v29, vcc
	v_cmp_class_f32_e32 vcc, v0, v228
	s_nop 1
	v_cndmask_b32_e32 v0, v28, v0, vcc
	v_div_scale_f32 v28, s[0:1], v0, v0, v176
	v_rcp_f32_e32 v29, v28
	s_nop 0
	v_fma_f32 v32, -v28, v29, 1.0
	v_fmac_f32_e32 v29, v32, v29
	v_div_scale_f32 v32, vcc, v176, v0, v176
	v_mul_f32_e32 v33, v32, v29
	v_fma_f32 v34, -v28, v33, v32
	v_fmac_f32_e32 v33, v34, v29
	v_fma_f32 v28, -v28, v33, v32
	v_div_fmas_f32 v28, v28, v29, v33
	global_load_dwordx4 v[130:133], v[150:151], off
	global_load_dwordx4 v[138:141], v[150:151], off offset:32
	global_load_dwordx4 v[142:145], v[150:151], off offset:64
	global_load_dwordx4 v[164:167], v[150:151], off offset:96
	global_load_dwordx4 v[170:173], v[150:151], off offset:128
	global_load_dwordx4 v[178:181], v[150:151], off offset:160
	global_load_dwordx4 v[182:185], v[150:151], off offset:192
	global_load_dwordx4 v[186:189], v[150:151], off offset:224
	global_load_dwordx4 v[190:193], v[150:151], off offset:256
	global_load_dwordx4 v[202:205], v[150:151], off offset:288
	global_load_dwordx4 v[210:213], v[150:151], off offset:320
	global_load_dwordx4 v[214:217], v[150:151], off offset:352
	global_load_dwordx4 v[218:221], v[150:151], off offset:384
	global_load_dwordx4 v[222:225], v[150:151], off offset:416
	global_load_dwordx4 v[240:243], v[150:151], off offset:448
	global_load_dwordx4 v[244:247], v[150:151], off offset:480
	v_div_fixup_f32 v0, v28, v0, v176
	v_lshlrev_b64 v[28:29], 12, v[152:153]
	v_lshl_add_u64 v[28:29], s[10:11], 0, v[28:29]
	v_pk_mul_f32 v[50:51], v[94:95], v[0:1] op_sel_hi:[1,0]
	v_pk_mul_f32 v[80:81], v[92:93], v[0:1] op_sel_hi:[1,0]
	v_lshl_add_u64 v[28:29], v[28:29], 0, s[36:37]
	v_lshl_add_u64 v[28:29], v[148:149], 1, v[28:29]
	v_pk_mul_f32 v[76:77], v[76:77], v[0:1] op_sel_hi:[1,0]
	v_pk_mul_f32 v[68:69], v[68:69], v[0:1] op_sel_hi:[1,0]
	v_pk_mul_f32 v[52:53], v[52:53], v[0:1] op_sel_hi:[1,0]
	v_pk_mul_f32 v[42:43], v[42:43], v[0:1] op_sel_hi:[1,0]
	v_pk_mul_f32 v[40:41], v[40:41], v[0:1] op_sel_hi:[1,0]
	v_pk_mul_f32 v[38:39], v[38:39], v[0:1] op_sel_hi:[1,0]
	v_pk_mul_f32 v[36:37], v[36:37], v[0:1] op_sel_hi:[1,0]
	v_pk_mul_f32 v[22:23], v[22:23], v[0:1] op_sel_hi:[1,0]
	v_pk_mul_f32 v[20:21], v[20:21], v[0:1] op_sel_hi:[1,0]
	v_pk_mul_f32 v[30:31], v[30:31], v[0:1] op_sel_hi:[1,0]
	v_pk_mul_f32 v[26:27], v[26:27], v[0:1] op_sel_hi:[1,0]
	v_pk_mul_f32 v[24:25], v[24:25], v[0:1] op_sel_hi:[1,0]
	s_waitcnt vmcnt(0)
; #define GAS __attribute__((address_space(1)))
; DI unsigned pk2(float lo, float hi) { f32x2 v = {lo, hi}; bf16x2_t b = __builtin_convertvector(v, bf16x2_t); return __builtin_bit_cast(unsigned, b); }
; DI void attn_unit_d32(const Ctx& C, const bf16_t* __restrict__ Z, bf16_t* __restrict__ Y, int b, int qsel, int hsel, bool ctxq, float lam, float post_scale, const float* subln, const float mref) {
;     ...
;         bf16_t* yp = Y + (size_t)qrow * DM + ycol;
; #pragma unroll
;         for (int d = 0; d < 4; ++d)
; #pragma unroll
;             for (int g = 0; g < 4; ++g) { const int dv = 32 * d + 8 * g + 4 * hh; const f32x4 gn = *(const GAS f32x4*)(subln + dv); const f32x4 v = r[d][g] * rs * gn;
;                 u32x2 wv; wv.x = pk2(v[0], v[1]); wv.y = pk2(v[2], v[3]); *(GAS u32x2*)(yp + dv) = wv; }
	v_pk_mul_f32 v[34:35], v[132:133], v[80:81]
	v_pk_mul_f32 v[32:33], v[130:131], v[50:51]
	v_pk_mul_f32 v[50:51], v[90:91], v[0:1] op_sel_hi:[1,0]
	v_cvt_pk_bf16_f32 v32, v32, v33
	v_cvt_pk_bf16_f32 v33, v34, v35
	global_store_dwordx2 v[28:29], v[32:33], off offset:3072
	v_pk_mul_f32 v[80:81], v[88:89], v[0:1] op_sel_hi:[1,0]
	v_pk_mul_f32 v[32:33], v[138:139], v[50:51]
	v_pk_mul_f32 v[34:35], v[140:141], v[80:81]
	v_cvt_pk_bf16_f32 v32, v32, v33
	v_cvt_pk_bf16_f32 v33, v34, v35
	global_store_dwordx2 v[28:29], v[32:33], off offset:3088
	v_pk_mul_f32 v[50:51], v[86:87], v[0:1] op_sel_hi:[1,0]
	v_pk_mul_f32 v[80:81], v[84:85], v[0:1] op_sel_hi:[1,0]
	v_pk_mul_f32 v[32:33], v[142:143], v[50:51]
	v_pk_mul_f32 v[34:35], v[144:145], v[80:81]
	v_cvt_pk_bf16_f32 v32, v32, v33
	v_cvt_pk_bf16_f32 v33, v34, v35
	global_store_dwordx2 v[28:29], v[32:33], off offset:3104
	v_pk_mul_f32 v[50:51], v[78:79], v[0:1] op_sel_hi:[1,0]
	v_pk_mul_f32 v[34:35], v[166:167], v[76:77]
	v_pk_mul_f32 v[32:33], v[164:165], v[50:51]
	v_pk_mul_f32 v[50:51], v[70:71], v[0:1] op_sel_hi:[1,0]
	v_cvt_pk_bf16_f32 v32, v32, v33
	v_cvt_pk_bf16_f32 v33, v34, v35
	global_store_dwordx2 v[28:29], v[32:33], off offset:3120
	v_pk_mul_f32 v[34:35], v[172:173], v[68:69]
	v_pk_mul_f32 v[32:33], v[170:171], v[50:51]
	v_pk_mul_f32 v[50:51], v[74:75], v[0:1] op_sel_hi:[1,0]
	v_cvt_pk_bf16_f32 v32, v32, v33
	v_cvt_pk_bf16_f32 v33, v34, v35
	global_store_dwordx2 v[28:29], v[32:33], off offset:3136
	v_pk_mul_f32 v[68:69], v[72:73], v[0:1] op_sel_hi:[1,0]
	v_pk_mul_f32 v[32:33], v[178:179], v[50:51]
	v_pk_mul_f32 v[34:35], v[180:181], v[68:69]
	v_cvt_pk_bf16_f32 v32, v32, v33
	v_cvt_pk_bf16_f32 v33, v34, v35
	global_store_dwordx2 v[28:29], v[32:33], off offset:3152
	v_pk_mul_f32 v[50:51], v[54:55], v[0:1] op_sel_hi:[1,0]
	v_pk_mul_f32 v[34:35], v[184:185], v[52:53]
	v_pk_mul_f32 v[32:33], v[182:183], v[50:51]
	v_pk_mul_f32 v[50:51], v[66:67], v[0:1] op_sel_hi:[1,0]
	v_cvt_pk_bf16_f32 v32, v32, v33
	v_cvt_pk_bf16_f32 v33, v34, v35
	global_store_dwordx2 v[28:29], v[32:33], off offset:3168
	v_pk_mul_f32 v[52:53], v[64:65], v[0:1] op_sel_hi:[1,0]
	v_pk_mul_f32 v[32:33], v[50:51], v[186:187]
	v_pk_mul_f32 v[34:35], v[52:53], v[188:189]
	v_cvt_pk_bf16_f32 v32, v32, v33
	v_cvt_pk_bf16_f32 v33, v34, v35
	global_store_dwordx2 v[28:29], v[32:33], off offset:3184
	v_pk_mul_f32 v[50:51], v[62:63], v[0:1] op_sel_hi:[1,0]
	v_pk_mul_f32 v[52:53], v[60:61], v[0:1] op_sel_hi:[1,0]
	v_pk_mul_f32 v[32:33], v[50:51], v[190:191]
	v_pk_mul_f32 v[34:35], v[52:53], v[192:193]
	v_cvt_pk_bf16_f32 v32, v32, v33
	v_cvt_pk_bf16_f32 v33, v34, v35
	global_store_dwordx2 v[28:29], v[32:33], off offset:3200
	v_pk_mul_f32 v[50:51], v[58:59], v[0:1] op_sel_hi:[1,0]
	v_pk_mul_f32 v[52:53], v[56:57], v[0:1] op_sel_hi:[1,0]
	v_pk_mul_f32 v[32:33], v[50:51], v[202:203]
	v_pk_mul_f32 v[34:35], v[52:53], v[204:205]
	v_cvt_pk_bf16_f32 v32, v32, v33
	v_cvt_pk_bf16_f32 v33, v34, v35
	global_store_dwordx2 v[28:29], v[32:33], off offset:3216
	v_pk_mul_f32 v[34:35], v[40:41], v[212:213]
	v_pk_mul_f32 v[32:33], v[42:43], v[210:211]
	s_nop 0
	v_cvt_pk_bf16_f32 v32, v32, v33
	v_cvt_pk_bf16_f32 v33, v34, v35
	global_store_dwordx2 v[28:29], v[32:33], off offset:3232
	v_pk_mul_f32 v[34:35], v[36:37], v[216:217]
	v_pk_mul_f32 v[32:33], v[38:39], v[214:215]
	s_nop 0
	v_cvt_pk_bf16_f32 v32, v32, v33
	v_cvt_pk_bf16_f32 v33, v34, v35
	global_store_dwordx2 v[28:29], v[32:33], off offset:3248
	v_pk_mul_f32 v[20:21], v[20:21], v[220:221]
	v_pk_mul_f32 v[22:23], v[22:23], v[218:219]
	v_pk_mul_f32 v[32:33], v[48:49], v[0:1] op_sel_hi:[1,0]
	v_cvt_pk_bf16_f32 v22, v22, v23
	v_cvt_pk_bf16_f32 v23, v20, v21
	global_store_dwordx2 v[28:29], v[22:23], off offset:3264
	v_pk_mul_f32 v[34:35], v[46:47], v[0:1] op_sel_hi:[1,0]
	v_pk_mul_f32 v[20:21], v[32:33], v[222:223]
	v_pk_mul_f32 v[22:23], v[34:35], v[224:225]
	v_cvt_pk_bf16_f32 v20, v20, v21
	v_cvt_pk_bf16_f32 v21, v22, v23
	global_store_dwordx2 v[28:29], v[20:21], off offset:3280
	v_pk_mul_f32 v[32:33], v[44:45], v[0:1] op_sel_hi:[1,0]
	v_pk_mul_f32 v[22:23], v[30:31], v[242:243]
	v_pk_mul_f32 v[20:21], v[32:33], v[240:241]
	s_nop 0
	v_cvt_pk_bf16_f32 v20, v20, v21
	v_cvt_pk_bf16_f32 v21, v22, v23
	global_store_dwordx2 v[28:29], v[20:21], off offset:3296
	v_pk_mul_f32 v[22:23], v[24:25], v[246:247]
	v_pk_mul_f32 v[20:21], v[26:27], v[244:245]
	s_nop 0
	v_cvt_pk_bf16_f32 v20, v20, v21
	v_cvt_pk_bf16_f32 v21, v22, v23
	global_store_dwordx2 v[28:29], v[20:21], off offset:3312
	s_branch .LBB0_541
